# phase +3 queue order: decode items and long attention pieces first (1:2), the 16 shortest attention pieces last in descending length
# baseline (speedup 1.0000x reference)
; __global__ void __launch_bounds__(512, 2) mk_fwd(Args args) {
;     ...
;                     for (;;) {
;                         if (F.tid == 0) *qslot = (int)__hip_atomic_fetch_add(actr, 1u, __ATOMIC_RELAXED, __HIP_MEMORY_SCOPE_AGENT);
;                         __syncthreads(); const int qi = __builtin_amdgcn_readfirstlane(*qslot); __syncthreads();
;                         if (qi >= 112) break;
;                         const int blk = qi / 7, pos = qi % 7;
;                         PH_PTRS; const int bh = u >> 5;
;                         if (pos == 0 || pos == 3 || pos == 5) {
;                             if (!(sel & 2)) continue;
;                             const int pi = 3 * blk + (pos == 0 ? 0 : pos == 3 ? 1 : 2);
;                             const float b2 = ((const float*)args.in[17])[lp * 4 + (bh & 3)] * LOG2E;
;                             bf16* AO = ACT + (size_t)1 * MPAD * BW;
;                             int qt, kb_lo, nkb; f32x4* part = nullptr; float* tp = nullptr;
;                             if (pi < 8) { qt = 15 - pi; kb_lo = 0; nkb = 2 * qt + 2; }
;                             else if (pi >= 40) { qt = 47 - pi; kb_lo = 0; nkb = 2 * qt + 2; }
;                             else { qt = 31 - ((pi - 8) >> 1); const int right = (pi - 8) & 1, q16 = qt - 16; kb_lo = right ? qt + 1 : 0; nkb = qt + 1;
;                                 part = (f32x4*)(wsp + WS_OPART) + ((size_t)((bh * 16 + q16) * 2 + right)) * 4096;
;                                 if (right) tp = (float*)(wsp + WS_TPART) + (size_t)(bh * 16 + q16) * 512; }
;                             attn_unit(Fp, bh >> 2, bh & 3, qt, kb_lo, nkb, QB, KB, VT, AO, b2, part, tp);
;                         } else {
;                             if (!(sel & 4)) continue;
;                             const int di = 4 * blk + (pos == 1 ? 0 : pos == 2 ? 1 : pos == 4 ? 2 : 3);
;                             decode_item(Fp, args, lp, bh * 64 + di, wsp);
;                         }
.LBB0_1037:
	s_or_b64 exec, exec, s[0:1]
	v_mov_b32_e32 v1, s72
	s_waitcnt vmcnt(0) lgkmcnt(0)
	s_barrier
	ds_read_b32 v1, v1
	s_mov_b64 s[0:1], -1
	s_waitcnt lgkmcnt(0)
	s_barrier
	v_readfirstlane_b32 s2, v1
	s_cmpk_gt_i32 s2, 0x6f
	s_cbranch_scc1 .LBB0_1032
	s_cmpk_lt_i32 s2, 0x60
	s_cbranch_scc0 .Lq3_tail
	s_mul_i32 s0, s2, 0xaaab
	s_lshr_b32 s0, s0, 17
	s_mul_i32 s1, s0, 3
	s_sub_i32 s1, s2, s1
	s_cmp_eq_u32 s1, 0
	s_cbranch_scc1 .Lq3_att
	s_lshl_b32 s0, s0, 1
	s_add_i32 s0, s0, s1
	s_add_i32 s0, s0, -1
	s_lshr_b32 s13, s0, 2
	s_and_b32 s14, s0, 3
	s_lshl_b32 s14, s14, 2
	s_lshr_b32 s14, 0x6421, s14
	s_and_b32 s14, s14, 15
	s_mul_i32 s13, s13, 7
	s_add_i32 s2, s13, s14
	s_branch .Lq3_done
.Lq3_tail:
	s_add_i32 s0, s2, 0xffffffc0
.Lq3_att:
	s_mul_i32 s13, s0, 0xaaab
	s_lshr_b32 s13, s13, 17
	s_mul_i32 s14, s13, 3
	s_sub_i32 s14, s0, s14
	s_lshl_b32 s14, s14, 2
	s_lshr_b32 s14, 0x530, s14
	s_and_b32 s14, s14, 15
	s_mul_i32 s13, s13, 7
	s_add_i32 s2, s13, s14
.Lq3_done:
	s_mov_b32 s12, s66
	s_mov_b64 s[10:11], s[62:63]
	s_mov_b32 s18, s94
	v_mov_b32_e32 v122, v210
	s_mov_b32 s0, s97
	v_mov_b32_e32 v1, v0
	s_mul_hi_i32 s0, s2, 0x92492493
	s_add_i32 s0, s0, s2
	s_lshr_b32 s1, s0, 31
	s_ashr_i32 s13, s0, 2
	s_add_i32 s13, s13, s1
	s_mul_i32 s0, s13, 7
	s_sub_i32 s14, s2, s0
	s_cmp_lt_i32 s14, 3
	s_cbranch_scc1 .LBB0_1041
	s_cmp_gt_i32 s14, 4
	s_cbranch_scc0 .LBB0_1042
	s_cmp_lg_u32 s14, 5
	s_mov_b64 s[0:1], -1
	s_cselect_b64 s[2:3], -1, 0
	s_cbranch_execz .LBB0_1043
	s_branch .LBB0_1044
